# StaticOrder::next: runtime division by group size (always 8) replaced by shift/mask
# baseline (speedup 1.0000x reference)
;     __device__ bool next(int i, Unit& u) const {
;         const long L = (long)i * G + c; if (L >= nwg) return false;
;         int wgid = (int)L; { const int q = nwg / NXCD, r = nwg % NXCD, xcd = wgid % NXCD, off = wgid / NXCD; wgid = (xcd < r ? xcd * (q + 1) : r * (q + 1) + (xcd - r) * q) + off; }
;         const int nig = WGM * nN, gid = wgid / nig, fm = gid * WGM, gsz = (nM - fm) < WGM ? (nM - fm) : WGM;
;         u.pm = fm + ((wgid % nig) % gsz); u.pn = (wgid % nig) / gsz; return true;
;     }
.LBB0_290:
	s_add_i32 s88, s88, 1
	s_mul_i32 s0, s88, s91
	s_mul_hi_u32 s1, s88, s3
	s_add_i32 s1, s1, s0
	s_mul_i32 s0, s88, s3
	s_add_u32 s70, s0, s2
	s_addc_u32 s71, s1, s92
	v_cmp_gt_i64_e32 vcc, s[70:71], v[146:147]
	v_cmp_lt_i64_e64 s[0:1], s[70:71], v[144:145]
	s_cbranch_vccnz .LBB0_292
	s_ashr_i32 s5, s70, 31
	s_lshr_b32 s5, s5, 29
	s_add_i32 s5, s70, s5
	s_ashr_i32 s8, s5, 3
	s_and_b32 s5, s5, -8
	s_sub_i32 s5, s70, s5
	s_cmp_lt_i32 s5, 0
	s_movk_i32 s9, 0xa1
	s_cselect_b32 s9, s9, 0xa0
	s_mul_i32 s5, s5, s9
	s_add_i32 s5, s5, s8
	s_mul_hi_i32 s8, s5, 0x66666667
	s_lshr_b32 s9, s8, 31
	s_ashr_i32 s8, s8, 5
	s_add_i32 s8, s8, s9
	s_lshl_b32 s9, s8, 3
	s_sub_i32 s50, 0x80, s9
	s_min_i32 s50, s50, 8
	s_mulk_i32 s8, 0x50
	s_sub_i32 s5, s5, s8
	s_ashr_i32 s66, s5, 3
	s_and_b32 s5, s5, 7
	s_add_i32 s68, s9, s5

;     __device__ bool next(int i, Unit& u) const {
;         const long L = (long)i * G + c; if (L >= nwg) return false;
;         int wgid = (int)L; { const int q = nwg / NXCD, r = nwg % NXCD, xcd = wgid % NXCD, off = wgid / NXCD; wgid = (xcd < r ? xcd * (q + 1) : r * (q + 1) + (xcd - r) * q) + off; }
;         const int nig = WGM * nN, gid = wgid / nig, fm = gid * WGM, gsz = (nM - fm) < WGM ? (nM - fm) : WGM;
;         u.pm = fm + ((wgid % nig) % gsz); u.pn = (wgid % nig) / gsz; return true;
;     }
.LBB0_518:
	s_ashr_i32 s52, s54, 3
	s_add_i32 s52, s56, s52
	s_ashr_i32 s53, s52, 31
	s_lshr_b32 s53, s53, 27
	s_add_i32 s53, s52, s53
	s_ashr_i32 s54, s53, 5
	s_lshl_b32 s54, s54, 3
	s_sub_i32 s55, 0x80, s54
	s_min_i32 s55, s55, 8
	s_andn2_b32 s53, s53, 31
	s_sub_i32 s53, s52, s53
	s_ashr_i32 s52, s53, 3
	s_and_b32 s53, s53, 7
	s_add_i32 s54, s54, s53

;     __device__ bool next(int i, Unit& u) const {
;         const long L = (long)i * G + c; if (L >= nwg) return false;
;         int wgid = (int)L; { const int q = nwg / NXCD, r = nwg % NXCD, xcd = wgid % NXCD, off = wgid / NXCD; wgid = (xcd < r ? xcd * (q + 1) : r * (q + 1) + (xcd - r) * q) + off; }
;         const int nig = WGM * nN, gid = wgid / nig, fm = gid * WGM, gsz = (nM - fm) < WGM ? (nM - fm) : WGM;
;         u.pm = fm + ((wgid % nig) % gsz); u.pn = (wgid % nig) / gsz; return true;
;     }
.LBB0_606:
	s_add_i32 s76, s76, 1
	s_mul_i32 s0, s76, s77
	s_mul_hi_u32 s1, s76, s3
	s_add_i32 s1, s1, s0
	s_mul_i32 s0, s76, s3
	s_add_u32 s10, s0, s2
	s_addc_u32 s11, s1, s68
	v_cmp_gt_i64_e32 vcc, s[10:11], v[144:145]
	v_cmp_lt_i64_e64 s[0:1], s[10:11], v[142:143]
	s_cbranch_vccnz .LBB0_608
	s_ashr_i32 s11, s10, 31
	s_lshr_b32 s11, s11, 29
	s_add_i32 s11, s10, s11
	s_ashr_i32 s12, s11, 3
	s_and_b32 s11, s11, -8
	s_sub_i32 s10, s10, s11
	s_cmp_lt_i32 s10, 0
	s_cselect_b32 s11, s69, 0x160
	s_mul_i32 s10, s10, s11
	s_add_i32 s10, s10, s12
	s_mul_hi_i32 s11, s10, 0x2e8ba2e9
	s_lshr_b32 s12, s11, 31
	s_ashr_i32 s11, s11, 5
	s_add_i32 s11, s11, s12
	s_lshl_b32 s12, s11, 3
	s_sub_i32 s13, 0x80, s12
	s_min_i32 s13, s13, 8
	s_mulk_i32 s11, 0xb0
	s_sub_i32 s10, s10, s11
	s_ashr_i32 s60, s10, 3
	s_and_b32 s10, s10, 7
	s_add_i32 s62, s12, s10

;     __device__ bool next(int i, Unit& u) const {
;         const long L = (long)i * G + c; if (L >= nwg) return false;
;         int wgid = (int)L; { const int q = nwg / NXCD, r = nwg % NXCD, xcd = wgid % NXCD, off = wgid / NXCD; wgid = (xcd < r ? xcd * (q + 1) : r * (q + 1) + (xcd - r) * q) + off; }
;         const int nig = WGM * nN, gid = wgid / nig, fm = gid * WGM, gsz = (nM - fm) < WGM ? (nM - fm) : WGM;
;         u.pm = fm + ((wgid % nig) % gsz); u.pn = (wgid % nig) / gsz; return true;
;     }
.LBB0_690:
	s_ashr_i32 s6, s18, 3
	s_add_i32 s6, s54, s6
	s_ashr_i32 s7, s6, 31
	s_lshr_b32 s7, s7, 27
	s_add_i32 s7, s6, s7
	s_ashr_i32 s18, s7, 5
	s_lshl_b32 s18, s18, 3
	s_sub_i32 s19, 0x80, s18
	s_min_i32 s19, s19, 8
	s_andn2_b32 s7, s7, 31
	s_sub_i32 s6, s6, s7
	s_ashr_i32 s69, s6, 3
	s_and_b32 s6, s6, 7
	s_add_i32 s70, s18, s6

;     __device__ bool next(int i, Unit& u) const {
;         const long L = (long)i * G + c; if (L >= nwg) return false;
;         int wgid = (int)L; { const int q = nwg / NXCD, r = nwg % NXCD, xcd = wgid % NXCD, off = wgid / NXCD; wgid = (xcd < r ? xcd * (q + 1) : r * (q + 1) + (xcd - r) * q) + off; }
;         const int nig = WGM * nN, gid = wgid / nig, fm = gid * WGM, gsz = (nM - fm) < WGM ? (nM - fm) : WGM;
;         u.pm = fm + ((wgid % nig) % gsz); u.pn = (wgid % nig) / gsz; return true;
;     }
.LBB0_784:
	s_add_i32 s54, s54, 1
	s_mul_i32 s8, s54, s15
	s_mul_hi_u32 s9, s54, s3
	s_add_i32 s9, s9, s8
	s_mul_i32 s8, s54, s3
	s_add_u32 s8, s8, s2
	s_addc_u32 s9, s9, s12
	v_cmp_gt_i64_e32 vcc, s[8:9], v[164:165]
	v_cmp_lt_i64_e64 s[10:11], s[8:9], v[162:163]
	s_cbranch_vccnz .LBB0_786
	s_ashr_i32 s9, s8, 31
	s_lshr_b32 s9, s9, 29
	s_add_i32 s9, s8, s9
	s_ashr_i32 s50, s9, 3
	s_and_b32 s9, s9, -8
	s_sub_i32 s8, s8, s9
	s_cmp_lt_i32 s8, 0
	s_movk_i32 s9, 0xa1
	s_cselect_b32 s9, s9, 0xa0
	s_mul_i32 s8, s8, s9
	s_add_i32 s8, s8, s50
	s_mul_hi_i32 s9, s8, 0x66666667
	s_lshr_b32 s50, s9, 31
	s_ashr_i32 s9, s9, 5
	s_add_i32 s9, s9, s50
	s_lshl_b32 s50, s9, 3
	s_sub_i32 s55, 0x80, s50
	s_min_i32 s55, s55, 8
	s_mulk_i32 s9, 0x50
	s_sub_i32 s8, s8, s9
	s_ashr_i32 s72, s8, 3
	s_and_b32 s8, s8, 7
	s_add_i32 s78, s50, s8

;     __device__ bool next(int i, Unit& u) const {
;         const long L = (long)i * G + c; if (L >= nwg) return false;
;         int wgid = (int)L; { const int q = nwg / NXCD, r = nwg % NXCD, xcd = wgid % NXCD, off = wgid / NXCD; wgid = (xcd < r ? xcd * (q + 1) : r * (q + 1) + (xcd - r) * q) + off; }
;         const int nig = WGM * nN, gid = wgid / nig, fm = gid * WGM, gsz = (nM - fm) < WGM ? (nM - fm) : WGM;
;         u.pm = fm + ((wgid % nig) % gsz); u.pn = (wgid % nig) / gsz; return true;
;     }
.LBB0_1337:
	s_ashr_i32 s16, s18, 3
	s_add_i32 s16, s20, s16
	s_ashr_i32 s17, s16, 31
	s_lshr_b32 s17, s17, 27
	s_add_i32 s17, s16, s17
	s_ashr_i32 s18, s17, 5
	s_lshl_b32 s18, s18, 3
	s_sub_i32 s19, 0x80, s18
	s_min_i32 s19, s19, 8
	s_andn2_b32 s17, s17, 31
	s_sub_i32 s17, s16, s17
	s_ashr_i32 s16, s17, 3
	s_and_b32 s17, s17, 7
	s_add_i32 s18, s18, s17

;     __device__ bool next(int i, Unit& u) const {
;         const long L = (long)i * G + c; if (L >= nwg) return false;
;         int wgid = (int)L; { const int q = nwg / NXCD, r = nwg % NXCD, xcd = wgid % NXCD, off = wgid / NXCD; wgid = (xcd < r ? xcd * (q + 1) : r * (q + 1) + (xcd - r) * q) + off; }
;         const int nig = WGM * nN, gid = wgid / nig, fm = gid * WGM, gsz = (nM - fm) < WGM ? (nM - fm) : WGM;
;         u.pm = fm + ((wgid % nig) % gsz); u.pn = (wgid % nig) / gsz; return true;
;     }
.LBB0_1425:
	s_add_i32 s54, s54, 1
	s_mul_i32 s0, s54, s55
	s_mul_hi_u32 s1, s54, s3
	s_add_i32 s1, s1, s0
	s_mul_i32 s0, s54, s3
	s_add_u32 s10, s0, s2
	s_addc_u32 s11, s1, s48
	v_cmp_gt_i64_e32 vcc, s[10:11], v[144:145]
	v_cmp_lt_i64_e64 s[0:1], s[10:11], v[142:143]
	s_cbranch_vccnz .LBB0_1427
	s_ashr_i32 s11, s10, 31
	s_lshr_b32 s11, s11, 29
	s_add_i32 s11, s10, s11
	s_ashr_i32 s12, s11, 3
	s_and_b32 s11, s11, -8
	s_sub_i32 s10, s10, s11
	s_cmp_lt_i32 s10, 0
	s_cselect_b32 s11, s49, 0x160
	s_mul_i32 s10, s10, s11
	s_add_i32 s10, s10, s12
	s_mul_hi_i32 s11, s10, 0x2e8ba2e9
	s_lshr_b32 s12, s11, 31
	s_ashr_i32 s11, s11, 5
	s_add_i32 s11, s11, s12
	s_lshl_b32 s12, s11, 3
	s_sub_i32 s13, 0x80, s12
	s_min_i32 s13, s13, 8
	s_mulk_i32 s11, 0xb0
	s_sub_i32 s10, s10, s11
	s_ashr_i32 s40, s10, 3
	s_and_b32 s10, s10, 7
	s_add_i32 s42, s12, s10

;     __device__ bool next(int i, Unit& u) const {
;         const long L = (long)i * G + c; if (L >= nwg) return false;
;         int wgid = (int)L; { const int q = nwg / NXCD, r = nwg % NXCD, xcd = wgid % NXCD, off = wgid / NXCD; wgid = (xcd < r ? xcd * (q + 1) : r * (q + 1) + (xcd - r) * q) + off; }
;         const int nig = WGM * nN, gid = wgid / nig, fm = gid * WGM, gsz = (nM - fm) < WGM ? (nM - fm) : WGM;
;         u.pm = fm + ((wgid % nig) % gsz); u.pn = (wgid % nig) / gsz; return true;
;     }
.LBB0_1507:
	s_ashr_i32 s0, s12, 3
	s_add_i32 s0, s18, s0
	s_ashr_i32 s1, s0, 31
	s_lshr_b32 s1, s1, 27
	s_add_i32 s1, s0, s1
	s_ashr_i32 s12, s1, 5
	s_lshl_b32 s12, s12, 3
	s_sub_i32 s13, 0x80, s12
	s_min_i32 s13, s13, 8
	s_andn2_b32 s1, s1, 31
	s_sub_i32 s0, s0, s1
	s_ashr_i32 s39, s0, 3
	s_and_b32 s0, s0, 7
	s_add_i32 s40, s12, s0
